# GLA core cross-chunk prefetch (two register sets by chunk parity); rowpass gain vector hoisted; MLA max via max3
# speedup vs baseline: 1.0960x; 1.0171x over previous
; DI void mla_attention(const int wave_s, const u16* __restrict__ QC, const u16* __restrict__ KF, const u16* __restrict__ Vt, u16* __restrict__ O, char* smem) {
;     ...
;           float mx = fmaxf(fmaxf(st[0], st[1]), fmaxf(st[2], st[3]));
; #pragma unroll
;           for (int i = 4; i < 16; i += 4) mx = fmaxf(mx, fmaxf(fmaxf(st[i], st[i + 1]), fmaxf(st[i + 2], st[i + 3])));
;           mx = xhalf_max(mx);
;           const float mn = fmaxf(m, mx);
;           const float alpha = __builtin_amdgcn_exp2f(m - mn);
;           float ps = 0.f;
; #pragma unroll
;           for (int i = 0; i < 16; ++i) {
;             st[i] = __builtin_amdgcn_exp2f(st[i] - mn);
;             ps += st[i];
;           }
;           ps = xhalf_sum(ps);
;           l = l * alpha + ps;
;           m = mn;
;           if (__builtin_amdgcn_ballot_w64(alpha != 1.f) != 0ull) {
; #pragma unroll
;             for (int i = 0; i < 16; ++i) { o0[i] *= alpha; o1[i] *= alpha; }
;           }
.LBB0_2398:
	s_nop 10
	v_max3_f32 v0, v34, v35, v36
	v_max3_f32 v121, v37, v38, v39
	v_max3_f32 v122, v40, v41, v42
	v_max3_f32 v123, v43, v44, v45
	v_max3_f32 v0, v0, v46, v47
	v_max3_f32 v121, v121, v48, v49
	v_max3_f32 v0, v0, v121, v122
	v_max_f32_e32 v0, v0, v123
	v_mov_b32_e32 v121, v0
	s_nop 1
	v_permlane32_swap_b32_e32 v0, v121
	v_max3_f32 v121, v119, v0, v121
	v_sub_f32_e32 v34, v34, v121
	v_sub_f32_e32 v0, v119, v121
	v_exp_f32_e32 v119, v34
	v_sub_f32_e32 v34, v35, v121
	v_exp_f32_e32 v122, v34
	v_sub_f32_e32 v34, v36, v121
	v_exp_f32_e32 v123, v34
	v_sub_f32_e32 v34, v37, v121
	v_exp_f32_e32 v124, v34
	v_sub_f32_e32 v35, v38, v121
	v_add_f32_e32 v34, 0, v119
	v_exp_f32_e32 v125, v35
	v_sub_f32_e32 v35, v39, v121
	v_add_f32_e32 v34, v122, v34
	v_exp_f32_e32 v126, v35
	v_sub_f32_e32 v35, v40, v121
	v_add_f32_e32 v34, v123, v34
	v_exp_f32_e32 v127, v35
	v_sub_f32_e32 v35, v41, v121
	v_add_f32_e32 v34, v124, v34
	v_exp_f32_e32 v128, v35
	v_add_f32_e32 v34, v125, v34
	v_add_f32_e32 v34, v126, v34
	v_add_f32_e32 v34, v127, v34
	v_add_f32_e32 v37, v128, v34
	v_sub_f32_e32 v34, v42, v121
	v_exp_f32_e32 v34, v34
	v_sub_f32_e32 v35, v43, v121
	v_exp_f32_e32 v35, v35
	v_sub_f32_e32 v36, v44, v121
	v_exp_f32_e32 v36, v36
	v_sub_f32_e32 v38, v45, v121
	v_exp_f32_e32 v38, v38
	v_sub_f32_e32 v39, v46, v121
	v_add_f32_e32 v37, v34, v37
	v_exp_f32_e32 v40, v39
	v_sub_f32_e32 v39, v47, v121
	v_add_f32_e32 v37, v35, v37
	v_exp_f32_e32 v41, v39
	v_sub_f32_e32 v39, v48, v121
	v_add_f32_e32 v37, v36, v37
	v_exp_f32_e32 v42, v39
	v_sub_f32_e32 v39, v49, v121
	v_add_f32_e32 v37, v38, v37
	v_exp_f32_e32 v43, v39
	v_add_f32_e32 v37, v40, v37
	v_add_f32_e32 v37, v41, v37
	v_exp_f32_e32 v0, v0
	v_add_f32_e32 v37, v42, v37
	v_add_f32_e32 v37, v43, v37
	v_mov_b32_e32 v39, v37
	s_nop 1
	v_permlane32_swap_b32_e32 v37, v39
	v_cmp_neq_f32_e32 vcc, 1.0, v0
	s_cbranch_vccz .LBB0_2400
	v_pk_mul_f32 v[32:33], v[32:33], v[0:1] op_sel_hi:[1,0]
	v_pk_mul_f32 v[30:31], v[30:31], v[0:1] op_sel_hi:[1,0]
	v_pk_mul_f32 v[28:29], v[28:29], v[0:1] op_sel_hi:[1,0]
	v_pk_mul_f32 v[26:27], v[26:27], v[0:1] op_sel_hi:[1,0]
	v_pk_mul_f32 v[24:25], v[24:25], v[0:1] op_sel_hi:[1,0]
	v_pk_mul_f32 v[22:23], v[22:23], v[0:1] op_sel_hi:[1,0]
	v_pk_mul_f32 v[20:21], v[20:21], v[0:1] op_sel_hi:[1,0]
	v_pk_mul_f32 v[18:19], v[18:19], v[0:1] op_sel_hi:[1,0]
	v_pk_mul_f32 v[16:17], v[16:17], v[0:1] op_sel_hi:[1,0]
	v_pk_mul_f32 v[14:15], v[14:15], v[0:1] op_sel_hi:[1,0]
	v_pk_mul_f32 v[12:13], v[12:13], v[0:1] op_sel_hi:[1,0]
	v_pk_mul_f32 v[10:11], v[10:11], v[0:1] op_sel_hi:[1,0]
	v_pk_mul_f32 v[8:9], v[8:9], v[0:1] op_sel_hi:[1,0]
	v_pk_mul_f32 v[6:7], v[6:7], v[0:1] op_sel_hi:[1,0]
	v_pk_mul_f32 v[4:5], v[4:5], v[0:1] op_sel_hi:[1,0]
	v_pk_mul_f32 v[2:3], v[2:3], v[0:1] op_sel_hi:[1,0]

; DI void mla_attention(const int wave_s, const u16* __restrict__ QC, const u16* __restrict__ KF, const u16* __restrict__ Vt, u16* __restrict__ O, char* smem) {
;     ...
;           float mx = fmaxf(fmaxf(st[0], st[1]), fmaxf(st[2], st[3]));
; #pragma unroll
;           for (int i = 4; i < 16; i += 4) mx = fmaxf(mx, fmaxf(fmaxf(st[i], st[i + 1]), fmaxf(st[i + 2], st[i + 3])));
;           mx = xhalf_max(mx);
;           const float mn = fmaxf(m, mx);
;           const float alpha = __builtin_amdgcn_exp2f(m - mn);
;           float ps = 0.f;
; #pragma unroll
;           for (int i = 0; i < 16; ++i) {
;             st[i] = __builtin_amdgcn_exp2f(st[i] - mn);
;             ps += st[i];
;           }
;           ps = xhalf_sum(ps);
;           l = l * alpha + ps;
;           m = mn;
;           if (__builtin_amdgcn_ballot_w64(alpha != 1.f) != 0ull) {
; #pragma unroll
;             for (int i = 0; i < 16; ++i) { o0[i] *= alpha; o1[i] *= alpha; }
;           }
.LBB0_2405:
	s_nop 10
	v_max3_f32 v0, v34, v35, v36
	v_max3_f32 v119, v37, v38, v39
	v_max3_f32 v120, v40, v41, v42
	v_max3_f32 v122, v43, v44, v45
	v_max3_f32 v0, v0, v46, v47
	v_max3_f32 v119, v119, v48, v49
	v_max3_f32 v0, v0, v119, v120
	v_max_f32_e32 v0, v0, v122
	v_mov_b32_e32 v119, v0
	s_nop 1
	v_permlane32_swap_b32_e32 v0, v119
	v_max3_f32 v119, v121, v0, v119
	v_sub_f32_e32 v34, v34, v119
	v_exp_f32_e32 v120, v34
	v_sub_f32_e32 v34, v35, v119
	v_sub_f32_e32 v0, v121, v119
	v_exp_f32_e32 v121, v34
	v_sub_f32_e32 v34, v36, v119
	v_exp_f32_e32 v122, v34
	v_sub_f32_e32 v34, v37, v119
	v_exp_f32_e32 v123, v34
	v_sub_f32_e32 v35, v38, v119
	v_add_f32_e32 v34, 0, v120
	v_exp_f32_e32 v124, v35
	v_sub_f32_e32 v35, v39, v119
	v_add_f32_e32 v34, v121, v34
	v_exp_f32_e32 v125, v35
	v_sub_f32_e32 v35, v40, v119
	v_add_f32_e32 v34, v122, v34
	v_exp_f32_e32 v126, v35
	v_sub_f32_e32 v35, v41, v119
	v_add_f32_e32 v34, v123, v34
	v_exp_f32_e32 v127, v35
	v_add_f32_e32 v34, v124, v34
	v_add_f32_e32 v34, v125, v34
	v_add_f32_e32 v34, v126, v34
	v_add_f32_e32 v37, v127, v34
	v_sub_f32_e32 v34, v42, v119
	v_exp_f32_e32 v34, v34
	v_sub_f32_e32 v35, v43, v119
	v_exp_f32_e32 v35, v35
	v_sub_f32_e32 v36, v44, v119
	v_exp_f32_e32 v36, v36
	v_sub_f32_e32 v38, v45, v119
	v_exp_f32_e32 v38, v38
	v_sub_f32_e32 v39, v46, v119
	v_add_f32_e32 v37, v34, v37
	v_exp_f32_e32 v40, v39
	v_sub_f32_e32 v39, v47, v119
	v_add_f32_e32 v37, v35, v37
	v_exp_f32_e32 v41, v39
	v_sub_f32_e32 v39, v48, v119
	v_add_f32_e32 v37, v36, v37
	v_exp_f32_e32 v42, v39
	v_sub_f32_e32 v39, v49, v119
	v_add_f32_e32 v37, v38, v37
	v_exp_f32_e32 v43, v39
	v_add_f32_e32 v37, v40, v37
	v_add_f32_e32 v37, v41, v37
	v_exp_f32_e32 v0, v0
	v_add_f32_e32 v37, v42, v37
	v_add_f32_e32 v37, v43, v37
	v_mov_b32_e32 v39, v37
	s_nop 1
	v_permlane32_swap_b32_e32 v37, v39
	v_cmp_neq_f32_e32 vcc, 1.0, v0
	s_cbranch_vccz .LBB0_2407
	v_pk_mul_f32 v[32:33], v[32:33], v[0:1] op_sel_hi:[1,0]
	v_pk_mul_f32 v[30:31], v[30:31], v[0:1] op_sel_hi:[1,0]
	v_pk_mul_f32 v[28:29], v[28:29], v[0:1] op_sel_hi:[1,0]
	v_pk_mul_f32 v[26:27], v[26:27], v[0:1] op_sel_hi:[1,0]
	v_pk_mul_f32 v[24:25], v[24:25], v[0:1] op_sel_hi:[1,0]
	v_pk_mul_f32 v[22:23], v[22:23], v[0:1] op_sel_hi:[1,0]
	v_pk_mul_f32 v[20:21], v[20:21], v[0:1] op_sel_hi:[1,0]
	v_pk_mul_f32 v[18:19], v[18:19], v[0:1] op_sel_hi:[1,0]
	v_pk_mul_f32 v[16:17], v[16:17], v[0:1] op_sel_hi:[1,0]
	v_pk_mul_f32 v[14:15], v[14:15], v[0:1] op_sel_hi:[1,0]
	v_pk_mul_f32 v[12:13], v[12:13], v[0:1] op_sel_hi:[1,0]
	v_pk_mul_f32 v[10:11], v[10:11], v[0:1] op_sel_hi:[1,0]
	v_pk_mul_f32 v[8:9], v[8:9], v[0:1] op_sel_hi:[1,0]
	v_pk_mul_f32 v[6:7], v[6:7], v[0:1] op_sel_hi:[1,0]
	v_pk_mul_f32 v[4:5], v[4:5], v[0:1] op_sel_hi:[1,0]
	v_pk_mul_f32 v[2:3], v[2:3], v[0:1] op_sel_hi:[1,0]

; #define MFMA32(a, b, c) __builtin_amdgcn_mfma_f32_32x32x16_bf16((a), (b), (c), 0, 0, 0)
; DI int crow(int i, int h) { return (i & 3) + 8 * (i >> 2) + 4 * h; }
; __global__ void __launch_bounds__(NTHR) mega(Params p) {
;     ...
;           const int b = u >> 5, hh = (u >> 3) & 3, dvs = u & 7;
;           const int r = lane & 31, h = lane >> 5;
;           for (int i = tid; i < 2 * 32 * 136 / 2; i += NTHR) ((unsigned*)St)[i] = 0u;
;           __syncthreads();
;           f32x16 Sacc = zero16();
;           const u16* vrow = Vt + ((size_t)(b * 4 + hh) * 256 + dvs * 32 + r) * SEQ + 8 * h;
;           const u16* kerow = KEt + ((size_t)(b * 4 + hh) * 128 + 32 * (wv & 3) + r) * SEQ + 8 * h;
;           for (int n = 0; n < 128; ++n) {
;             const size_t tok0 = (size_t)b * SEQ + n * 64;
;             if (wv < 4) {
;               const float* ex = GEX + ((size_t)(b * 128 + n) * 4 + hh) * 128 + 32 * wv;
; #pragma unroll
;               for (int i = 0; i < 16; ++i) Sacc[i] *= ex[crow(i, h)];
; #pragma unroll
;               for (int s = 0; s < 4; ++s) {
;                 const bf16x8 a = *(const bf16x8*)(kerow + n * 64 + 16 * s);
;                 const bf16x8 bv = *(const bf16x8*)(vrow + n * 64 + 16 * s);
;                 Sacc = MFMA32(a, bv, Sacc);
;               }
;               u16* sd = St + ((n + 1) & 1) * 32 * 136 + r * 136 + 32 * wv + 4 * h;
; #pragma unroll
;               for (int g = 0; g < 4; ++g) {
;                 uint2 pk;
;                 pk.x = pack2(Sacc[4 * g], Sacc[4 * g + 1]);
;                 pk.y = pack2(Sacc[4 * g + 2], Sacc[4 * g + 3]);
;                 *(uint2*)(sd + 8 * g) = pk;
;               }
;             } else if (wv < 6) {
;               const int ti = wv - 4;
;               f32x16 acc = zero16();
;               const u16* arow = ATT + (tok0 + 32 * ti + r) * 256 + hh * 64 + 8 * h;
; #pragma unroll
;               for (int s = 0; s < 4; ++s) {
;                 const bf16x8 a = *(const bf16x8*)(arow + 16 * s);
;                 const bf16x8 bv = *(const bf16x8*)(vrow + n * 64 + 16 * s);
;                 acc = MFMA32(a, bv, acc);
;               }
;               const u16* qrow = QD + (tok0 + 32 * ti + r) * 512 + hh * 128 + 8 * h;
.LBB0_2733:
	s_or_b64 exec, exec, s[10:11]
	s_ashr_i32 s12, s15, 5
	s_ashr_i32 s13, s12, 31
	s_bfe_u32 s22, s15, 0x20003
	s_lshl_b32 s10, s14, 1
	s_lshl_b64 s[16:17], s[12:13], 13
	s_lshl_b32 s21, s22, 9
	s_and_b32 s19, s10, 0x1c0
	v_lshl_add_u64 v[2:3], v[44:45], 0, s[16:17]
	s_lshl_b32 s24, s12, 2
	s_lshl_b32 s18, s12, 7
	s_lshl_b64 s[12:13], s[12:13], 24
	s_or_b32 s20, s19, s21
	v_lshlrev_b64 v[4:5], 10, v[2:3]
	v_lshlrev_b64 v[2:3], 9, v[2:3]
	s_lshl_b32 s10, s22, 7
	s_mov_b32 s11, s67
	s_or_b32 s12, s12, s20
	s_ashr_i32 s19, s18, 31
	v_lshl_add_u64 v[2:3], v[42:43], 0, v[2:3]
	v_lshl_add_u64 v[50:51], s[12:13], 0, v[38:39]
	s_lshl_b64 s[12:13], s[18:19], 11
	v_lshl_add_u64 v[56:57], v[2:3], 0, s[10:11]
	s_or_b32 s10, s24, s22
	s_or_b32 s12, s12, s21
	v_lshl_add_u64 v[2:3], v[36:37], 0, s[16:17]
	s_ashr_i32 s11, s10, 31
	v_lshl_add_u64 v[52:53], s[12:13], 0, v[40:41]
	v_lshlrev_b64 v[2:3], 11, v[2:3]
	s_lshl_b64 s[12:13], s[10:11], 21
	s_lshl_b64 s[10:11], s[10:11], 8
	s_and_b32 s23, s14, 0xe0
	v_lshl_add_u64 v[2:3], v[46:47], 0, v[2:3]
	s_mov_b32 s21, s67
	v_or_b32_e32 v0, s10, v34
	v_lshl_add_u64 v[58:59], s[20:21], 0, v[2:3]
	v_mov_b32_e32 v3, s11
	v_or_b32_e32 v2, s23, v0
	s_lshl_b32 s66, s22, 8
	v_lshl_add_u64 v[4:5], v[42:43], 0, v[4:5]
	v_lshlrev_b64 v[2:3], 14, v[2:3]
	v_lshl_add_u64 v[54:55], v[4:5], 0, s[66:67]
	v_lshl_add_u64 v[62:63], v[42:43], 0, v[2:3]
	v_mov_b32_e32 v2, v1
	v_mov_b32_e32 v3, v1
	v_mov_b32_e32 v4, v1
	v_mov_b32_e32 v5, v1
	v_mov_b32_e32 v6, v1
	v_mov_b32_e32 v7, v1
	v_mov_b32_e32 v8, v1
	v_mov_b32_e32 v9, v1
	v_mov_b32_e32 v10, v1
	v_mov_b32_e32 v11, v1
	v_mov_b32_e32 v12, v1
	v_mov_b32_e32 v13, v1
	v_mov_b32_e32 v14, v1
	v_mov_b32_e32 v15, v1
	v_mov_b32_e32 v0, v1
	v_mov_b64_e32 v[16:17], v[14:15]
	v_lshl_add_u64 v[60:61], v[48:49], 0, s[12:13]
	s_mov_b32 s12, 0
	v_mov_b64_e32 v[14:15], v[12:13]
	v_mov_b64_e32 v[12:13], v[10:11]
	v_mov_b64_e32 v[10:11], v[8:9]
	v_mov_b64_e32 v[8:9], v[6:7]
	v_mov_b64_e32 v[6:7], v[4:5]
	v_mov_b64_e32 v[4:5], v[2:3]
	v_mov_b64_e32 v[2:3], v[0:1]
	s_and_b64 vcc, exec, s[6:7]
	s_cbranch_vccz .Lgla_preB
	s_andn2_b64 vcc, exec, s[8:9]
	s_cbranch_vccnz .Lgla_pre_done
	v_lshl_add_u64 v[18:19], s[86:87], 0, v[56:57]
	v_add_co_u32_e32 v76, vcc, 0x17800000, v18
	v_lshl_add_u64 v[22:23], s[86:87], 0, v[62:63]
	s_nop 0
	v_addc_co_u32_e32 v77, vcc, 0, v19, vcc
	v_add_co_u32_e32 v78, vcc, 0xb000000, v22
	v_lshl_add_u64 v[18:19], s[86:87], 0, v[54:55]
	s_nop 0
	v_addc_co_u32_e32 v79, vcc, 0, v23, vcc
	v_add_co_u32_e32 v80, vcc, 0x13800000, v18
	s_nop 1
	v_addc_co_u32_e32 v81, vcc, 0, v19, vcc
	global_load_dwordx4 v[100:103], v[76:77], off
	global_load_dwordx4 v[104:107], v[78:79], off
	global_load_dwordx4 v[108:111], v[76:77], off offset:32
	global_load_dwordx4 v[112:115], v[78:79], off offset:32
	global_load_dwordx4 v[116:119], v[76:77], off offset:64
	global_load_dwordx4 v[120:123], v[78:79], off offset:64
	global_load_dwordx4 v[124:127], v[76:77], off offset:96
	global_load_dwordx4 v[128:131], v[78:79], off offset:96
	global_load_dwordx4 v[132:135], v[80:81], off
	global_load_dwordx4 v[136:139], v[80:81], off offset:32
	global_load_dwordx4 v[140:143], v[80:81], off offset:64
	global_load_dwordx4 v[144:147], v[80:81], off offset:96
	global_load_dwordx4 v[148:151], v[80:81], off offset:128
	global_load_dwordx4 v[152:155], v[80:81], off offset:160
	global_load_dwordx4 v[156:159], v[80:81], off offset:192
	global_load_dwordx4 v[160:163], v[80:81], off offset:224
	s_branch .Lgla_pre_done
.Lgla_preB:
	v_lshl_add_u64 v[84:85], s[86:87], 0, v[52:53]
	v_add_co_u32_e32 v84, vcc, 0x18800000, v84
	v_lshl_add_u64 v[86:87], s[86:87], 0, v[60:61]
	s_nop 0
	v_addc_co_u32_e32 v85, vcc, 0, v85, vcc
	v_add_co_u32_e32 v86, vcc, 0x15800000, v86
	v_lshl_add_u64 v[88:89], s[86:87], 0, v[62:63]
	s_nop 0
	v_addc_co_u32_e32 v87, vcc, 0, v87, vcc
	v_add_co_u32_e32 v88, vcc, 0xb000000, v88
	s_nop 1
	v_addc_co_u32_e32 v89, vcc, 0, v89, vcc
	global_load_dwordx4 v[148:151], v[84:85], off
	global_load_dwordx4 v[152:155], v[84:85], off offset:32
	global_load_dwordx4 v[156:159], v[84:85], off offset:64
	global_load_dwordx4 v[160:163], v[84:85], off offset:96
	global_load_dwordx4 v[100:103], v[86:87], off
	global_load_dwordx4 v[104:107], v[88:89], off
	global_load_dwordx4 v[108:111], v[86:87], off offset:32
	global_load_dwordx4 v[112:115], v[88:89], off offset:32
	global_load_dwordx4 v[116:119], v[86:87], off offset:64
	global_load_dwordx4 v[120:123], v[88:89], off offset:64
	global_load_dwordx4 v[124:127], v[86:87], off offset:96
	global_load_dwordx4 v[128:131], v[88:89], off offset:96
.Lgla_pre_done:
	s_mov_b64 s[10:11], 0x800
	v_lshl_add_u64 v[52:53], v[52:53], 0, s[10:11]
	s_mov_b64 s[10:11], 0x10000
	v_lshl_add_u64 v[54:55], v[54:55], 0, s[10:11]
	v_lshl_add_u64 v[56:57], v[56:57], 0, s[70:71]
	v_lshl_add_u64 v[60:61], v[60:61], 0, s[62:63]
	v_lshl_add_u64 v[62:63], v[62:63], 0, s[62:63]
	s_waitcnt lgkmcnt(0)
	s_barrier
	s_branch .LBB0_2735

; #define MFMA32(a, b, c) __builtin_amdgcn_mfma_f32_32x32x16_bf16((a), (b), (c), 0, 0, 0)
; __global__ void __launch_bounds__(NTHR) mega(Params p) {
;     ...
;             } else if (wv < 6) {
;               const int ti = wv - 4;
;               f32x16 acc = zero16();
;               const u16* arow = ATT + (tok0 + 32 * ti + r) * 256 + hh * 64 + 8 * h;
; #pragma unroll
;               for (int s = 0; s < 4; ++s) {
;                 const bf16x8 a = *(const bf16x8*)(arow + 16 * s);
;                 const bf16x8 bv = *(const bf16x8*)(vrow + n * 64 + 16 * s);
;                 acc = MFMA32(a, bv, acc);
;               }
;               const u16* qrow = QD + (tok0 + 32 * ti + r) * 512 + hh * 128 + 8 * h;
;               const u16* ss = St + (n & 1) * 32 * 136 + r * 136 + 8 * h;
; #pragma unroll
;               for (int s = 0; s < 8; ++s) {
;                 const bf16x8 a = *(const bf16x8*)(qrow + 16 * s);
;                 const bf16x8 bs = *(const bf16x8*)(ss + 16 * s);
;                 acc = MFMA32(a, bs, acc);
;               }
.LBB0_2735:
	s_and_b64 vcc, exec, s[6:7]
	s_cbranch_vccz .Lgla_B
	s_andn2_b64 vcc, exec, s[8:9]
	s_cbranch_vccnz .LBB0_2734
	s_bitcmp1_b32 s12, 5
	s_cbranch_scc1 .Lgla_A1
	s_and_b32 s10, s12, 32
	s_mulk_i32 s10, 0x110
	v_add_u32_e32 v0, s10, v35
	ds_read_b128 v[68:71], v0
	ds_read_b128 v[72:75], v0 offset:32
	ds_read_b128 v[96:99], v0 offset:64
	ds_read_b128 v[164:167], v0 offset:96
	s_cmpk_eq_i32 s12, 0xfe0
	s_cbranch_scc1 .Lgla_A0_last
	v_lshl_add_u64 v[18:19], s[86:87], 0, v[56:57]
	v_add_co_u32_e32 v76, vcc, 0x17800000, v18
	v_lshl_add_u64 v[22:23], s[86:87], 0, v[62:63]
	s_nop 0
	v_addc_co_u32_e32 v77, vcc, 0, v19, vcc
	v_add_co_u32_e32 v78, vcc, 0xb000000, v22
	v_lshl_add_u64 v[18:19], s[86:87], 0, v[54:55]
	s_nop 0
	v_addc_co_u32_e32 v79, vcc, 0, v23, vcc
	v_add_co_u32_e32 v80, vcc, 0x13800000, v18
	s_nop 1
	v_addc_co_u32_e32 v81, vcc, 0, v19, vcc
	global_load_dwordx4 v[176:179], v[76:77], off
	global_load_dwordx4 v[180:183], v[78:79], off
	global_load_dwordx4 v[184:187], v[76:77], off offset:32
	global_load_dwordx4 v[188:191], v[78:79], off offset:32
	global_load_dwordx4 v[192:195], v[76:77], off offset:64
	global_load_dwordx4 v[196:199], v[78:79], off offset:64
	global_load_dwordx4 v[200:203], v[76:77], off offset:96
	global_load_dwordx4 v[204:207], v[78:79], off offset:96
	global_load_dwordx4 v[208:211], v[80:81], off
	global_load_dwordx4 v[212:215], v[80:81], off offset:32
	global_load_dwordx4 v[216:219], v[80:81], off offset:64
	global_load_dwordx4 v[220:223], v[80:81], off offset:96
	global_load_dwordx4 v[224:227], v[80:81], off offset:128
	global_load_dwordx4 v[84:87], v[80:81], off offset:160
	global_load_dwordx4 v[88:91], v[80:81], off offset:192
	global_load_dwordx4 v[92:95], v[80:81], off offset:224
	s_waitcnt vmcnt(16)
	s_branch .Lgla_A0_go

; #define MFMA32(a, b, c) __builtin_amdgcn_mfma_f32_32x32x16_bf16((a), (b), (c), 0, 0, 0)
; DI int crow(int i, int h) { return (i & 3) + 8 * (i >> 2) + 4 * h; }
; DI u16 f2bf(float a) { return (u16)(pack2(a, 0.f) & 0xffffu); }
; __global__ void __launch_bounds__(NTHR) mega(Params p) {
;     ...
;               const int ti = wv - 4;
;               f32x16 acc = zero16();
;               const u16* arow = ATT + (tok0 + 32 * ti + r) * 256 + hh * 64 + 8 * h;
; #pragma unroll
;               for (int s = 0; s < 4; ++s) {
;                 const bf16x8 a = *(const bf16x8*)(arow + 16 * s);
;                 const bf16x8 bv = *(const bf16x8*)(vrow + n * 64 + 16 * s);
;                 acc = MFMA32(a, bv, acc);
;               }
;               const u16* qrow = QD + (tok0 + 32 * ti + r) * 512 + hh * 128 + 8 * h;
;               const u16* ss = St + (n & 1) * 32 * 136 + r * 136 + 8 * h;
; #pragma unroll
;               for (int s = 0; s < 8; ++s) {
;                 const bf16x8 a = *(const bf16x8*)(qrow + 16 * s);
;                 const bf16x8 bs = *(const bf16x8*)(ss + 16 * s);
;                 acc = MFMA32(a, bs, acc);
;               }
; #pragma unroll
;               for (int i = 0; i < 16; ++i) O[(tok0 + 32 * ti + crow(i, h)) * 1024 + hh * 256 + dvs * 32 + r] = f2bf(acc[i]);
.Lgla_A0_go:
	v_mfma_f32_32x32x16_bf16 v[18:33], v[100:103], v[104:107], 0
	v_mfma_f32_32x32x16_bf16 v[18:33], v[108:111], v[112:115], v[18:33]
	v_mfma_f32_32x32x16_bf16 v[18:33], v[116:119], v[120:123], v[18:33]
	v_mfma_f32_32x32x16_bf16 v[18:33], v[124:127], v[128:131], v[18:33]
	s_waitcnt lgkmcnt(3)
	v_mfma_f32_32x32x16_bf16 v[18:33], v[132:135], v[68:71], v[18:33]
	ds_read_b128 v[68:71], v0 offset:128
	s_waitcnt lgkmcnt(3)
	v_mfma_f32_32x32x16_bf16 v[18:33], v[136:139], v[72:75], v[18:33]
	ds_read_b128 v[72:75], v0 offset:160
	s_waitcnt lgkmcnt(3)
	v_mfma_f32_32x32x16_bf16 v[18:33], v[140:143], v[96:99], v[18:33]
	ds_read_b128 v[96:99], v0 offset:192
	s_waitcnt lgkmcnt(3)
	v_mfma_f32_32x32x16_bf16 v[18:33], v[144:147], v[164:167], v[18:33]
	ds_read_b128 v[164:167], v0 offset:224
	s_waitcnt lgkmcnt(3)
	v_mfma_f32_32x32x16_bf16 v[18:33], v[148:151], v[68:71], v[18:33]
	s_waitcnt lgkmcnt(2)
	v_mfma_f32_32x32x16_bf16 v[18:33], v[152:155], v[72:75], v[18:33]
	s_waitcnt lgkmcnt(1)
	v_mfma_f32_32x32x16_bf16 v[18:33], v[156:159], v[96:99], v[18:33]
	s_waitcnt lgkmcnt(0)
	v_mfma_f32_32x32x16_bf16 v[18:33], v[160:163], v[164:167], v[18:33]
	s_mov_b32 s10, 0x19001000
	v_lshl_add_u64 v[68:69], s[86:87], 0, v[58:59]
	s_nop 10
	v_cvt_pk_bf16_f32 v0, v18, s0
	global_store_short v[68:69], v0, off
	v_cvt_pk_bf16_f32 v0, v19, s0
	v_lshl_add_u64 v[18:19], s[86:87], 0, v[50:51]
	v_add_co_u32_e32 v68, vcc, s51, v18
	s_nop 1
	v_addc_co_u32_e32 v69, vcc, 0, v19, vcc
	global_store_short v[68:69], v0, off offset:2048
	v_add_co_u32_e32 v68, vcc, s10, v18
	v_cvt_pk_bf16_f32 v0, v20, s0
	s_nop 0
	v_addc_co_u32_e32 v69, vcc, 0, v19, vcc
	s_mov_b32 s10, 0x19004000
	global_store_short v[68:69], v0, off
	v_cvt_pk_bf16_f32 v0, v21, s0
	v_add_co_u32_e32 v20, vcc, s10, v18
	global_store_short v[68:69], v0, off offset:2048
	v_cvt_pk_bf16_f32 v0, v22, s0
	v_addc_co_u32_e32 v21, vcc, 0, v19, vcc
	global_store_short v[20:21], v0, off
	v_cvt_pk_bf16_f32 v0, v23, s0
	s_mov_b32 s10, 0x19005000
	global_store_short v[20:21], v0, off offset:2048
	v_add_co_u32_e32 v20, vcc, s10, v18
	v_cvt_pk_bf16_f32 v0, v24, s0
	s_nop 0
	v_addc_co_u32_e32 v21, vcc, 0, v19, vcc
	global_store_short v[20:21], v0, off
	v_cvt_pk_bf16_f32 v0, v25, s0
	s_mov_b32 s10, 0x19008000
	global_store_short v[20:21], v0, off offset:2048
	v_add_co_u32_e32 v20, vcc, s10, v18
	v_cvt_pk_bf16_f32 v0, v26, s0
	s_nop 0
	v_addc_co_u32_e32 v21, vcc, 0, v19, vcc
	global_store_short v[20:21], v0, off
	v_cvt_pk_bf16_f32 v0, v27, s0
	s_mov_b32 s10, 0x19009000
	global_store_short v[20:21], v0, off offset:2048
	v_add_co_u32_e32 v20, vcc, s10, v18
	v_cvt_pk_bf16_f32 v0, v28, s0
	s_nop 0
	v_addc_co_u32_e32 v21, vcc, 0, v19, vcc
	global_store_short v[20:21], v0, off
	v_cvt_pk_bf16_f32 v0, v29, s0
	global_store_short v[20:21], v0, off offset:2048
	v_add_co_u32_e32 v20, vcc, 0x1900c000, v18
	v_cvt_pk_bf16_f32 v0, v30, s0
	s_nop 0
	v_addc_co_u32_e32 v21, vcc, 0, v19, vcc
	global_store_short v[20:21], v0, off
	v_cvt_pk_bf16_f32 v0, v31, s0
	v_add_co_u32_e32 v18, vcc, 0x1900d000, v18
	global_store_short v[20:21], v0, off offset:2048
	v_cvt_pk_bf16_f32 v0, v32, s0
	v_addc_co_u32_e32 v19, vcc, 0, v19, vcc
	global_store_short v[18:19], v0, off
	v_cvt_pk_bf16_f32 v0, v33, s0
	global_store_short v[18:19], v0, off offset:2048
	s_branch .LBB0_2734
.Lgla_A1:
	s_and_b32 s10, s12, 32
	s_mulk_i32 s10, 0x110
	v_add_u32_e32 v0, s10, v35
	ds_read_b128 v[68:71], v0
	ds_read_b128 v[72:75], v0 offset:32
	ds_read_b128 v[96:99], v0 offset:64
	ds_read_b128 v[164:167], v0 offset:96
	s_cmpk_eq_i32 s12, 0xfe0
	s_cbranch_scc1 .Lgla_A1_last
	v_lshl_add_u64 v[18:19], s[86:87], 0, v[56:57]
	v_add_co_u32_e32 v76, vcc, 0x17800000, v18
	v_lshl_add_u64 v[22:23], s[86:87], 0, v[62:63]
	s_nop 0
	v_addc_co_u32_e32 v77, vcc, 0, v19, vcc
	v_add_co_u32_e32 v78, vcc, 0xb000000, v22
	v_lshl_add_u64 v[18:19], s[86:87], 0, v[54:55]
	s_nop 0
	v_addc_co_u32_e32 v79, vcc, 0, v23, vcc
	v_add_co_u32_e32 v80, vcc, 0x13800000, v18
	s_nop 1
	v_addc_co_u32_e32 v81, vcc, 0, v19, vcc
	global_load_dwordx4 v[100:103], v[76:77], off
	global_load_dwordx4 v[104:107], v[78:79], off
	global_load_dwordx4 v[108:111], v[76:77], off offset:32
	global_load_dwordx4 v[112:115], v[78:79], off offset:32
	global_load_dwordx4 v[116:119], v[76:77], off offset:64
	global_load_dwordx4 v[120:123], v[78:79], off offset:64
	global_load_dwordx4 v[124:127], v[76:77], off offset:96
	global_load_dwordx4 v[128:131], v[78:79], off offset:96
	global_load_dwordx4 v[132:135], v[80:81], off
	global_load_dwordx4 v[136:139], v[80:81], off offset:32
	global_load_dwordx4 v[140:143], v[80:81], off offset:64
	global_load_dwordx4 v[144:147], v[80:81], off offset:96
	global_load_dwordx4 v[148:151], v[80:81], off offset:128
	global_load_dwordx4 v[152:155], v[80:81], off offset:160
	global_load_dwordx4 v[156:159], v[80:81], off offset:192
	global_load_dwordx4 v[160:163], v[80:81], off offset:224
	s_waitcnt vmcnt(16)
	s_branch .Lgla_A1_go

; #define MFMA32(a, b, c) __builtin_amdgcn_mfma_f32_32x32x16_bf16((a), (b), (c), 0, 0, 0)
; DI int crow(int i, int h) { return (i & 3) + 8 * (i >> 2) + 4 * h; }
; DI u16 f2bf(float a) { return (u16)(pack2(a, 0.f) & 0xffffu); }
; __global__ void __launch_bounds__(NTHR) mega(Params p) {
;     ...
;             if (wv < 4) {
;               const float* ex = GEX + ((size_t)(b * 128 + n) * 4 + hh) * 128 + 32 * wv;
; #pragma unroll
;               for (int i = 0; i < 16; ++i) Sacc[i] *= ex[crow(i, h)];
; #pragma unroll
;               for (int s = 0; s < 4; ++s) {
;                 const bf16x8 a = *(const bf16x8*)(kerow + n * 64 + 16 * s);
;                 const bf16x8 bv = *(const bf16x8*)(vrow + n * 64 + 16 * s);
;                 Sacc = MFMA32(a, bv, Sacc);
;               }
;     ...
;               const int ti = wv - 4;
;               f32x16 acc = zero16();
;               const u16* arow = ATT + (tok0 + 32 * ti + r) * 256 + hh * 64 + 8 * h;
; #pragma unroll
;               for (int s = 0; s < 4; ++s) {
;                 const bf16x8 a = *(const bf16x8*)(arow + 16 * s);
;                 const bf16x8 bv = *(const bf16x8*)(vrow + n * 64 + 16 * s);
;                 acc = MFMA32(a, bv, acc);
;               }
;               const u16* qrow = QD + (tok0 + 32 * ti + r) * 512 + hh * 128 + 8 * h;
;               const u16* ss = St + (n & 1) * 32 * 136 + r * 136 + 8 * h;
; #pragma unroll
;               for (int s = 0; s < 8; ++s) {
;                 const bf16x8 a = *(const bf16x8*)(qrow + 16 * s);
;                 const bf16x8 bs = *(const bf16x8*)(ss + 16 * s);
;                 acc = MFMA32(a, bs, acc);
;               }
; #pragma unroll
;               for (int i = 0; i < 16; ++i) O[(tok0 + 32 * ti + crow(i, h)) * 1024 + hh * 256 + dvs * 32 + r] = f2bf(acc[i]);
.Lgla_A1_go:
	v_mfma_f32_32x32x16_bf16 v[18:33], v[176:179], v[180:183], 0
	v_mfma_f32_32x32x16_bf16 v[18:33], v[184:187], v[188:191], v[18:33]
	v_mfma_f32_32x32x16_bf16 v[18:33], v[192:195], v[196:199], v[18:33]
	v_mfma_f32_32x32x16_bf16 v[18:33], v[200:203], v[204:207], v[18:33]
	s_waitcnt lgkmcnt(3)
	v_mfma_f32_32x32x16_bf16 v[18:33], v[208:211], v[68:71], v[18:33]
	ds_read_b128 v[68:71], v0 offset:128
	s_waitcnt lgkmcnt(3)
	v_mfma_f32_32x32x16_bf16 v[18:33], v[212:215], v[72:75], v[18:33]
	ds_read_b128 v[72:75], v0 offset:160
	s_waitcnt lgkmcnt(3)
	v_mfma_f32_32x32x16_bf16 v[18:33], v[216:219], v[96:99], v[18:33]
	ds_read_b128 v[96:99], v0 offset:192
	s_waitcnt lgkmcnt(3)
	v_mfma_f32_32x32x16_bf16 v[18:33], v[220:223], v[164:167], v[18:33]
	ds_read_b128 v[164:167], v0 offset:224
	s_waitcnt lgkmcnt(3)
	v_mfma_f32_32x32x16_bf16 v[18:33], v[224:227], v[68:71], v[18:33]
	s_waitcnt lgkmcnt(2)
	v_mfma_f32_32x32x16_bf16 v[18:33], v[84:87], v[72:75], v[18:33]
	s_waitcnt lgkmcnt(1)
	v_mfma_f32_32x32x16_bf16 v[18:33], v[88:91], v[96:99], v[18:33]
	s_waitcnt lgkmcnt(0)
	v_mfma_f32_32x32x16_bf16 v[18:33], v[92:95], v[164:167], v[18:33]
	s_mov_b32 s10, 0x19001000
	v_lshl_add_u64 v[68:69], s[86:87], 0, v[58:59]
	s_nop 10
	v_cvt_pk_bf16_f32 v0, v18, s0
	global_store_short v[68:69], v0, off
	v_cvt_pk_bf16_f32 v0, v19, s0
	v_lshl_add_u64 v[18:19], s[86:87], 0, v[50:51]
	v_add_co_u32_e32 v68, vcc, s51, v18
	s_nop 1
	v_addc_co_u32_e32 v69, vcc, 0, v19, vcc
	global_store_short v[68:69], v0, off offset:2048
	v_add_co_u32_e32 v68, vcc, s10, v18
	v_cvt_pk_bf16_f32 v0, v20, s0
	s_nop 0
	v_addc_co_u32_e32 v69, vcc, 0, v19, vcc
	s_mov_b32 s10, 0x19004000
	global_store_short v[68:69], v0, off
	v_cvt_pk_bf16_f32 v0, v21, s0
	v_add_co_u32_e32 v20, vcc, s10, v18
	global_store_short v[68:69], v0, off offset:2048
	v_cvt_pk_bf16_f32 v0, v22, s0
	v_addc_co_u32_e32 v21, vcc, 0, v19, vcc
	global_store_short v[20:21], v0, off
	v_cvt_pk_bf16_f32 v0, v23, s0
	s_mov_b32 s10, 0x19005000
	global_store_short v[20:21], v0, off offset:2048
	v_add_co_u32_e32 v20, vcc, s10, v18
	v_cvt_pk_bf16_f32 v0, v24, s0
	s_nop 0
	v_addc_co_u32_e32 v21, vcc, 0, v19, vcc
	global_store_short v[20:21], v0, off
	v_cvt_pk_bf16_f32 v0, v25, s0
	s_mov_b32 s10, 0x19008000
	global_store_short v[20:21], v0, off offset:2048
	v_add_co_u32_e32 v20, vcc, s10, v18
	v_cvt_pk_bf16_f32 v0, v26, s0
	s_nop 0
	v_addc_co_u32_e32 v21, vcc, 0, v19, vcc
	global_store_short v[20:21], v0, off
	v_cvt_pk_bf16_f32 v0, v27, s0
	s_mov_b32 s10, 0x19009000
	global_store_short v[20:21], v0, off offset:2048
	v_add_co_u32_e32 v20, vcc, s10, v18
	v_cvt_pk_bf16_f32 v0, v28, s0
	s_nop 0
	v_addc_co_u32_e32 v21, vcc, 0, v19, vcc
	global_store_short v[20:21], v0, off
	v_cvt_pk_bf16_f32 v0, v29, s0
	global_store_short v[20:21], v0, off offset:2048
	v_add_co_u32_e32 v20, vcc, 0x1900c000, v18
	v_cvt_pk_bf16_f32 v0, v30, s0
	s_nop 0
	v_addc_co_u32_e32 v21, vcc, 0, v19, vcc
	global_store_short v[20:21], v0, off
	v_cvt_pk_bf16_f32 v0, v31, s0
	v_add_co_u32_e32 v18, vcc, 0x1900d000, v18
	global_store_short v[20:21], v0, off offset:2048
	v_cvt_pk_bf16_f32 v0, v32, s0
	v_addc_co_u32_e32 v19, vcc, 0, v19, vcc
	global_store_short v[18:19], v0, off
	v_cvt_pk_bf16_f32 v0, v33, s0
	global_store_short v[18:19], v0, off offset:2048
	s_branch .LBB0_2734
.Lgla_B:
	s_bitcmp1_b32 s12, 5
	s_cbranch_scc1 .Lgla_B1
	s_cmpk_eq_i32 s12, 0xfe0
	s_cbranch_scc1 .Lgla_B0_last
	v_lshl_add_u64 v[84:85], s[86:87], 0, v[52:53]
	v_add_co_u32_e32 v84, vcc, 0x18800000, v84
	v_lshl_add_u64 v[86:87], s[86:87], 0, v[60:61]
	s_nop 0
	v_addc_co_u32_e32 v85, vcc, 0, v85, vcc
	v_add_co_u32_e32 v86, vcc, 0x15800000, v86
	v_lshl_add_u64 v[88:89], s[86:87], 0, v[62:63]
	s_nop 0
	v_addc_co_u32_e32 v87, vcc, 0, v87, vcc
	v_add_co_u32_e32 v88, vcc, 0xb000000, v88
	s_nop 1
	v_addc_co_u32_e32 v89, vcc, 0, v89, vcc
	global_load_dwordx4 v[132:135], v[84:85], off
	global_load_dwordx4 v[136:139], v[84:85], off offset:32
	global_load_dwordx4 v[140:143], v[84:85], off offset:64
	global_load_dwordx4 v[144:147], v[84:85], off offset:96
	global_load_dwordx4 v[176:179], v[86:87], off
	global_load_dwordx4 v[180:183], v[88:89], off
	global_load_dwordx4 v[184:187], v[86:87], off offset:32
	global_load_dwordx4 v[188:191], v[88:89], off offset:32
	global_load_dwordx4 v[192:195], v[86:87], off offset:64
	global_load_dwordx4 v[196:199], v[88:89], off offset:64
	global_load_dwordx4 v[200:203], v[86:87], off offset:96
	global_load_dwordx4 v[204:207], v[88:89], off offset:96
	s_waitcnt vmcnt(12)
	s_branch .Lgla_B0_go

; #define MFMA32(a, b, c) __builtin_amdgcn_mfma_f32_32x32x16_bf16((a), (b), (c), 0, 0, 0)
; DI int crow(int i, int h) { return (i & 3) + 8 * (i >> 2) + 4 * h; }
; __global__ void __launch_bounds__(NTHR) mega(Params p) {
;     ...
;               const float* ex = GEX + ((size_t)(b * 128 + n) * 4 + hh) * 128 + 32 * wv;
; #pragma unroll
;               for (int i = 0; i < 16; ++i) Sacc[i] *= ex[crow(i, h)];
; #pragma unroll
;               for (int s = 0; s < 4; ++s) {
;                 const bf16x8 a = *(const bf16x8*)(kerow + n * 64 + 16 * s);
;                 const bf16x8 bv = *(const bf16x8*)(vrow + n * 64 + 16 * s);
;                 Sacc = MFMA32(a, bv, Sacc);
;               }
;               u16* sd = St + ((n + 1) & 1) * 32 * 136 + r * 136 + 32 * wv + 4 * h;
; #pragma unroll
;               for (int g = 0; g < 4; ++g) {
;                 uint2 pk;
;                 pk.x = pack2(Sacc[4 * g], Sacc[4 * g + 1]);
;                 pk.y = pack2(Sacc[4 * g + 2], Sacc[4 * g + 3]);
;                 *(uint2*)(sd + 8 * g) = pk;
;               }
.Lgla_B0_go:
	v_pk_mul_f32 v[2:3], v[2:3], v[148:149]
	v_pk_mul_f32 v[4:5], v[4:5], v[150:151]
	v_pk_mul_f32 v[6:7], v[6:7], v[152:153]
	v_pk_mul_f32 v[8:9], v[8:9], v[154:155]
	v_pk_mul_f32 v[10:11], v[10:11], v[156:157]
	v_pk_mul_f32 v[12:13], v[12:13], v[158:159]
	v_pk_mul_f32 v[14:15], v[14:15], v[160:161]
	v_pk_mul_f32 v[16:17], v[16:17], v[162:163]
	s_andn2_b32 s10, 32, s12
	s_mulk_i32 s10, 0x110
	v_add_u32_e32 v0, s10, v64
	v_mfma_f32_32x32x16_bf16 v[2:17], v[100:103], v[104:107], v[2:17]
	v_mfma_f32_32x32x16_bf16 v[2:17], v[108:111], v[112:115], v[2:17]
	v_mfma_f32_32x32x16_bf16 v[2:17], v[116:119], v[120:123], v[2:17]
	v_mfma_f32_32x32x16_bf16 v[2:17], v[124:127], v[128:131], v[2:17]
	s_nop 11
	v_cvt_pk_bf16_f32 v18, v2, v3
	v_cvt_pk_bf16_f32 v19, v4, v5
	v_cvt_pk_bf16_f32 v20, v6, v7
	v_cvt_pk_bf16_f32 v21, v8, v9
	ds_write2_b64 v0, v[18:19], v[20:21] offset1:2
	v_cvt_pk_bf16_f32 v18, v10, v11
	v_cvt_pk_bf16_f32 v19, v12, v13
	v_cvt_pk_bf16_f32 v20, v14, v15
	v_cvt_pk_bf16_f32 v21, v16, v17
	ds_write2_b64 v0, v[18:19], v[20:21] offset0:4 offset1:6
	s_branch .LBB0_2734
.Lgla_B1:
	s_cmpk_eq_i32 s12, 0xfe0
	s_cbranch_scc1 .Lgla_B1_last
	v_lshl_add_u64 v[84:85], s[86:87], 0, v[52:53]
	v_add_co_u32_e32 v84, vcc, 0x18800000, v84
	v_lshl_add_u64 v[86:87], s[86:87], 0, v[60:61]
	s_nop 0
	v_addc_co_u32_e32 v85, vcc, 0, v85, vcc
	v_add_co_u32_e32 v86, vcc, 0x15800000, v86
	v_lshl_add_u64 v[88:89], s[86:87], 0, v[62:63]
	s_nop 0
	v_addc_co_u32_e32 v87, vcc, 0, v87, vcc
	v_add_co_u32_e32 v88, vcc, 0xb000000, v88
	s_nop 1
	v_addc_co_u32_e32 v89, vcc, 0, v89, vcc
	global_load_dwordx4 v[148:151], v[84:85], off
	global_load_dwordx4 v[152:155], v[84:85], off offset:32
	global_load_dwordx4 v[156:159], v[84:85], off offset:64
	global_load_dwordx4 v[160:163], v[84:85], off offset:96
	global_load_dwordx4 v[100:103], v[86:87], off
	global_load_dwordx4 v[104:107], v[88:89], off
	global_load_dwordx4 v[108:111], v[86:87], off offset:32
	global_load_dwordx4 v[112:115], v[88:89], off offset:32
	global_load_dwordx4 v[116:119], v[86:87], off offset:64
	global_load_dwordx4 v[120:123], v[88:89], off offset:64
	global_load_dwordx4 v[124:127], v[86:87], off offset:96
	global_load_dwordx4 v[128:131], v[88:89], off offset:96
	s_waitcnt vmcnt(12)
	s_branch .Lgla_B1_go

; #define MFMA32(a, b, c) __builtin_amdgcn_mfma_f32_32x32x16_bf16((a), (b), (c), 0, 0, 0)
; DI int crow(int i, int h) { return (i & 3) + 8 * (i >> 2) + 4 * h; }
; __global__ void __launch_bounds__(NTHR) mega(Params p) {
;     ...
;               const float* ex = GEX + ((size_t)(b * 128 + n) * 4 + hh) * 128 + 32 * wv;
; #pragma unroll
;               for (int i = 0; i < 16; ++i) Sacc[i] *= ex[crow(i, h)];
; #pragma unroll
;               for (int s = 0; s < 4; ++s) {
;                 const bf16x8 a = *(const bf16x8*)(kerow + n * 64 + 16 * s);
;                 const bf16x8 bv = *(const bf16x8*)(vrow + n * 64 + 16 * s);
;                 Sacc = MFMA32(a, bv, Sacc);
;               }
;               u16* sd = St + ((n + 1) & 1) * 32 * 136 + r * 136 + 32 * wv + 4 * h;
; #pragma unroll
;               for (int g = 0; g < 4; ++g) {
;                 uint2 pk;
;                 pk.x = pack2(Sacc[4 * g], Sacc[4 * g + 1]);
;                 pk.y = pack2(Sacc[4 * g + 2], Sacc[4 * g + 3]);
;                 *(uint2*)(sd + 8 * g) = pk;
;               }
.Lgla_B1_go:
	v_pk_mul_f32 v[2:3], v[2:3], v[132:133]
	v_pk_mul_f32 v[4:5], v[4:5], v[134:135]
	v_pk_mul_f32 v[6:7], v[6:7], v[136:137]
	v_pk_mul_f32 v[8:9], v[8:9], v[138:139]
	v_pk_mul_f32 v[10:11], v[10:11], v[140:141]
	v_pk_mul_f32 v[12:13], v[12:13], v[142:143]
	v_pk_mul_f32 v[14:15], v[14:15], v[144:145]
	v_pk_mul_f32 v[16:17], v[16:17], v[146:147]
	s_andn2_b32 s10, 32, s12
	s_mulk_i32 s10, 0x110
	v_add_u32_e32 v0, s10, v64
	v_mfma_f32_32x32x16_bf16 v[2:17], v[176:179], v[180:183], v[2:17]
	v_mfma_f32_32x32x16_bf16 v[2:17], v[184:187], v[188:191], v[2:17]
	v_mfma_f32_32x32x16_bf16 v[2:17], v[192:195], v[196:199], v[2:17]
	v_mfma_f32_32x32x16_bf16 v[2:17], v[200:203], v[204:207], v[2:17]
	s_nop 11
	v_cvt_pk_bf16_f32 v18, v2, v3
	v_cvt_pk_bf16_f32 v19, v4, v5
	v_cvt_pk_bf16_f32 v20, v6, v7
	v_cvt_pk_bf16_f32 v21, v8, v9
	ds_write2_b64 v0, v[18:19], v[20:21] offset1:2
	v_cvt_pk_bf16_f32 v18, v10, v11
	v_cvt_pk_bf16_f32 v19, v12, v13
	v_cvt_pk_bf16_f32 v20, v14, v15
	v_cvt_pk_bf16_f32 v21, v16, v17
	ds_write2_b64 v0, v[18:19], v[20:21] offset0:4 offset1:6
	s_branch .LBB0_2734

; DI float bflo(unsigned u) { return __uint_as_float(u << 16); }
; DI float bfhi(unsigned u) { return __uint_as_float(u & 0xffff0000u); }
; DI void rowpass(const int wave_s, const float* __restrict__ xin, u16* __restrict__ X, const u16* __restrict__ Y, const float* __restrict__ gpost,
;                 const float* __restrict__ gpre, u16* __restrict__ HN, float* __restrict__ outf) {
;     ...
;   for (int row = blockIdx.x * 8 + wv; row < TOK; row += gridDim.x * 8) {
;     float4 x[4];
;     if (Y) {
;       float4 y[4];
;       float ss = 0.f;
; #pragma unroll
;       for (int j = 0; j < 4; ++j) {
;         const uint2 yu = *(const uint2*)(Y + (size_t)row * 1024 + j * 256 + lane * 4);
;         y[j] = make_float4(bflo(yu.x), bfhi(yu.x), bflo(yu.y), bfhi(yu.y));
;         ss += y[j].x * y[j].x + y[j].y * y[j].y + y[j].z * y[j].z + y[j].w * y[j].w;
;       }
;       ss = wsum(ss);
;       const float rs = rsqrtf(ss * (1.f / 1024.f) + 1e-6f);
; #pragma unroll
;       for (int j = 0; j < 4; ++j) {
;         const float4 g = *(const float4*)(gpost + j * 256 + lane * 4);
;         const uint2 xu = *(const uint2*)(X + (size_t)row * 1024 + j * 256 + lane * 4);
;     ...
;       for (int j = 0; j < 4; ++j) {
;         const float4 g = *(const float4*)(gpre + j * 256 + lane * 4);
.LBB0_3258:
	v_readlane_b32 s4, v254, 10
	v_readlane_b32 s5, v254, 11
	s_waitcnt lgkmcnt(0)
	s_barrier
	s_add_u32 s10, s86, 0x2000000
	s_addc_u32 s11, s87, 0
	s_nop 0
	global_load_dwordx2 v[2:3], v1, s[4:5] offset:24
	s_mov_b32 s4, s6
	v_readlane_b32 s5, v254, 26
	s_add_i32 s6, s4, s5
	s_mul_i32 s12, s93, 0x1800
	s_mov_b32 s13, s67
	v_mov_b32_e32 v0, v171
	s_cmpk_gt_i32 s6, 0x7fff
	s_waitcnt vmcnt(0)
	v_readfirstlane_b32 s4, v3
	v_readfirstlane_b32 s5, v2
	s_cbranch_scc1 .LBB0_3264
	s_lshl_b64 s[8:9], s[12:13], 2
	s_add_u32 s8, s5, s8
	v_lshlrev_b32_e32 v18, 2, v0
	s_addc_u32 s9, s4, s9
	v_ashrrev_i32_e32 v19, 31, v18
	v_lshl_add_u64 v[22:23], v[18:19], 2, s[8:9]
	s_mov_b64 s[4:5], 0x1000
	v_lshl_add_u64 v[14:15], v[22:23], 0, s[4:5]
	s_movk_i32 s4, 0x1000
	v_add_co_u32_e32 v10, vcc, s4, v22
	v_lshlrev_b64 v[24:25], 1, v[18:19]
	s_nop 0
	v_addc_co_u32_e32 v11, vcc, 0, v23, vcc
	flat_load_dwordx4 v[2:5], v[14:15] offset:1024
	flat_load_dwordx4 v[6:9], v[14:15] offset:2048
	s_nop 0
	flat_load_dwordx4 v[10:13], v[10:11]
	s_nop 0
	flat_load_dwordx4 v[14:17], v[14:15] offset:3072
	s_cmp_lg_u64 s[0:1], 0
	s_mov_b64 s[4:5], 0x2000
	v_lshl_add_u64 v[18:19], s[88:89], 0, v[24:25]
	v_lshl_add_u64 v[20:21], s[10:11], 0, v[24:25]
	s_cselect_b64 s[8:9], -1, 0
	v_lshl_add_u64 v[22:23], v[22:23], 0, s[4:5]
	v_lshl_add_u64 v[24:25], s[0:1], 0, v[24:25]
	s_mov_b32 s16, 0x800000
	flat_load_dwordx4 v[100:103], v[22:23]
	flat_load_dwordx4 v[104:107], v[22:23] offset:1024
	flat_load_dwordx4 v[108:111], v[22:23] offset:2048
	flat_load_dwordx4 v[112:115], v[22:23] offset:3072
	s_branch .LBB0_3261

; DI float bflo(unsigned u) { return __uint_as_float(u << 16); }
; DI float bfhi(unsigned u) { return __uint_as_float(u & 0xffff0000u); }
; DI void rowpass(const int wave_s, const float* __restrict__ xin, u16* __restrict__ X, const u16* __restrict__ Y, const float* __restrict__ gpost,
;                 const float* __restrict__ gpre, u16* __restrict__ HN, float* __restrict__ outf) {
;     ...
;     if (Y) {
;       float4 y[4];
;       float ss = 0.f;
; #pragma unroll
;       for (int j = 0; j < 4; ++j) {
;         const uint2 yu = *(const uint2*)(Y + (size_t)row * 1024 + j * 256 + lane * 4);
;         y[j] = make_float4(bflo(yu.x), bfhi(yu.x), bflo(yu.y), bfhi(yu.y));
;         ss += y[j].x * y[j].x + y[j].y * y[j].y + y[j].z * y[j].z + y[j].w * y[j].w;
;       }
;       ss = wsum(ss);
;       const float rs = rsqrtf(ss * (1.f / 1024.f) + 1e-6f);
; #pragma unroll
;       for (int j = 0; j < 4; ++j) {
;         const float4 g = *(const float4*)(gpost + j * 256 + lane * 4);
;         const uint2 xu = *(const uint2*)(X + (size_t)row * 1024 + j * 256 + lane * 4);
;         x[j] = make_float4(bflo(xu.x), bfhi(xu.x), bflo(xu.y), bfhi(xu.y));
;         x[j].x += y[j].x * rs * g.x; x[j].y += y[j].y * rs * g.y; x[j].z += y[j].z * rs * g.z; x[j].w += y[j].w * rs * g.w;
;       }
;     } else {
; #pragma unroll
;       for (int j = 0; j < 4; ++j) x[j] = *(const float4*)(xin + (size_t)row * 1024 + j * 256 + lane * 4);
;     }
;     float ss2 = 0.f;
; #pragma unroll
;     for (int j = 0; j < 4; ++j) {
;       if (outf) *(float4*)(outf + (size_t)row * 1024 + j * 256 + lane * 4) = x[j];
;       else { uint2 xp; xp.x = pack2(x[j].x, x[j].y); xp.y = pack2(x[j].z, x[j].w); *(uint2*)(X + (size_t)row * 1024 + j * 256 + lane * 4) = xp; }
;       ss2 += x[j].x * x[j].x + x[j].y * x[j].y + x[j].z * x[j].z + x[j].w * x[j].w;
;     }
.LBB0_3261:
	s_ashr_i32 s7, s6, 31
	s_lshl_b64 s[14:15], s[6:7], 11
	v_lshl_add_u64 v[26:27], v[18:19], 0, s[14:15]
	flat_load_dwordx2 v[28:29], v[26:27]
	flat_load_dwordx2 v[30:31], v[26:27] offset:512
	flat_load_dwordx2 v[32:33], v[26:27] offset:1024
	s_nop 0
	flat_load_dwordx2 v[26:27], v[26:27] offset:1536
	v_lshl_add_u64 v[44:45], v[20:21], 0, s[14:15]
	flat_load_dwordx2 v[34:35], v[44:45]
	flat_load_dwordx2 v[36:37], v[44:45] offset:512
	flat_load_dwordx2 v[38:39], v[44:45] offset:1024
	flat_load_dwordx2 v[40:41], v[44:45] offset:1536
	s_andn2_b64 vcc, exec, s[8:9]
	s_waitcnt vmcnt(0) lgkmcnt(0)
	v_and_b32_e32 v43, 0xffff0000, v28
	v_and_b32_e32 v47, 0xffff0000, v30
	v_lshlrev_b32_e32 v42, 16, v28
	v_lshlrev_b32_e32 v46, 16, v30
	v_and_b32_e32 v49, 0xffff0000, v32
	v_and_b32_e32 v51, 0xffff0000, v26
	v_mov_b32_e32 v58, v43
	v_mov_b32_e32 v59, v47
	v_lshlrev_b32_e32 v28, 16, v29
	v_lshlrev_b32_e32 v30, 16, v31
	v_lshlrev_b32_e32 v48, 16, v32
	v_lshlrev_b32_e32 v50, 16, v26
	v_mov_b32_e32 v56, v42
	v_mov_b32_e32 v57, v46
	v_mov_b32_e32 v66, v49
	v_mov_b32_e32 v67, v51
	v_pk_mul_f32 v[58:59], v[58:59], v[58:59]
	v_and_b32_e32 v29, 0xffff0000, v29
	v_and_b32_e32 v31, 0xffff0000, v31
	v_lshlrev_b32_e32 v32, 16, v33
	v_lshlrev_b32_e32 v26, 16, v27
	v_mov_b32_e32 v52, v28
	v_mov_b32_e32 v53, v30
	v_mov_b32_e32 v64, v48
	v_mov_b32_e32 v65, v50
	v_pk_mul_f32 v[66:67], v[66:67], v[66:67]
	v_pk_fma_f32 v[56:57], v[56:57], v[56:57], v[58:59]
	v_and_b32_e32 v33, 0xffff0000, v33
	v_and_b32_e32 v27, 0xffff0000, v27
	v_mov_b32_e32 v54, v29
	v_mov_b32_e32 v55, v31
	v_mov_b32_e32 v60, v32
	v_mov_b32_e32 v61, v26
	v_pk_fma_f32 v[58:59], v[64:65], v[64:65], v[66:67]
	v_pk_fma_f32 v[52:53], v[52:53], v[52:53], v[56:57]
	v_mov_b32_e32 v62, v33
	v_mov_b32_e32 v63, v27
	v_pk_fma_f32 v[56:57], v[60:61], v[60:61], v[58:59]
	v_pk_fma_f32 v[52:53], v[54:55], v[54:55], v[52:53]
	v_pk_fma_f32 v[54:55], v[62:63], v[62:63], v[56:57]
	v_add_f32_e32 v0, v52, v53
	v_add_f32_e32 v0, v0, v54
	v_add_f32_e32 v0, v0, v55
	v_mov_b32_e32 v52, v0
	s_nop 1
	v_permlane32_swap_b32_e32 v0, v52
	v_lshlrev_b32_e32 v56, 16, v38
	v_lshlrev_b32_e32 v58, 16, v39
	v_and_b32_e32 v59, 0xffff0000, v39
	v_lshlrev_b32_e32 v54, 16, v36
	s_waitcnt lgkmcnt(0)
	v_add_f32_e32 v0, v0, v52
	v_mov_b32_e32 v52, v0
	s_nop 1
	v_permlane16_swap_b32_e32 v0, v52
	v_lshlrev_b32_e32 v60, 16, v40
	v_lshlrev_b32_e32 v62, 16, v41
	v_and_b32_e32 v63, 0xffff0000, v41
	s_waitcnt lgkmcnt(0)
	v_add_f32_e32 v0, v0, v52
	s_nop 1
	v_mov_b32_dpp v53, v0 row_ror:8 row_mask:0xf bank_mask:0xf
	v_lshlrev_b32_e32 v52, 16, v34
	s_waitcnt lgkmcnt(0)
	v_add_f32_e32 v0, v0, v53
	s_nop 1
	v_mov_b32_dpp v55, v0 row_ror:4 row_mask:0xf bank_mask:0xf
	v_and_b32_e32 v53, 0xffff0000, v34
	v_lshlrev_b32_e32 v34, 16, v35
	v_and_b32_e32 v35, 0xffff0000, v35
	s_waitcnt lgkmcnt(0)
	v_add_f32_e32 v0, v0, v55
	s_nop 1
	v_mov_b32_dpp v57, v0 row_ror:2 row_mask:0xf bank_mask:0xf
	v_and_b32_e32 v55, 0xffff0000, v36
	v_lshlrev_b32_e32 v36, 16, v37
	v_and_b32_e32 v37, 0xffff0000, v37
	s_waitcnt lgkmcnt(0)
	v_add_f32_e32 v0, v0, v57
	s_nop 1
	v_mov_b32_dpp v61, v0 row_ror:1 row_mask:0xf bank_mask:0xf
	v_and_b32_e32 v57, 0xffff0000, v38
	s_waitcnt lgkmcnt(0)
	v_add_f32_e32 v0, v0, v61
	v_fmamk_f32 v0, v0, 0x3a800000, v170
	v_mul_f32_e32 v38, 0x4b800000, v0
	v_cmp_gt_f32_e64 s[4:5], s16, v0
	v_and_b32_e32 v61, 0xffff0000, v40
	s_nop 0
	v_cndmask_b32_e64 v0, v0, v38, s[4:5]
	v_rsq_f32_e32 v0, v0
	s_nop 0
	v_mul_f32_e32 v38, 0x45800000, v0
	v_cndmask_b32_e64 v0, v0, v38, s[4:5]
	v_pk_mul_f32 v[38:39], v[0:1], v[42:43] op_sel_hi:[0,1]
	v_pk_mul_f32 v[28:29], v[0:1], v[28:29] op_sel_hi:[0,1]
	v_pk_mul_f32 v[46:47], v[0:1], v[46:47] op_sel_hi:[0,1]
	v_pk_mul_f32 v[30:31], v[0:1], v[30:31] op_sel_hi:[0,1]
	v_pk_mul_f32 v[48:49], v[0:1], v[48:49] op_sel_hi:[0,1]
	v_pk_mul_f32 v[32:33], v[0:1], v[32:33] op_sel_hi:[0,1]
	v_pk_mul_f32 v[50:51], v[0:1], v[50:51] op_sel_hi:[0,1]
	v_pk_mul_f32 v[26:27], v[0:1], v[26:27] op_sel_hi:[0,1]
	v_pk_fma_f32 v[42:43], v[10:11], v[38:39], v[52:53]
	v_pk_fma_f32 v[40:41], v[12:13], v[28:29], v[34:35]
	v_pk_fma_f32 v[38:39], v[2:3], v[46:47], v[54:55]
	v_pk_fma_f32 v[36:37], v[4:5], v[30:31], v[36:37]
	v_pk_fma_f32 v[34:35], v[6:7], v[48:49], v[56:57]
	v_pk_fma_f32 v[32:33], v[32:33], v[8:9], v[58:59]
	v_pk_fma_f32 v[30:31], v[50:51], v[14:15], v[60:61]
	v_pk_fma_f32 v[28:29], v[26:27], v[16:17], v[62:63]
	v_cvt_pk_bf16_f32 v26, v42, v43
	v_cvt_pk_bf16_f32 v27, v40, v41
	v_cvt_pk_bf16_f32 v46, v38, v39
	v_cvt_pk_bf16_f32 v47, v36, v37
	v_cvt_pk_bf16_f32 v48, v34, v35
	v_cvt_pk_bf16_f32 v49, v32, v33
	v_cvt_pk_bf16_f32 v50, v30, v31
	v_cvt_pk_bf16_f32 v51, v28, v29
	flat_store_dwordx2 v[44:45], v[26:27]
	flat_store_dwordx2 v[44:45], v[46:47] offset:512
	flat_store_dwordx2 v[44:45], v[48:49] offset:1024
	flat_store_dwordx2 v[44:45], v[50:51] offset:1536
	s_cbranch_vccnz .LBB0_3260
; DI void rowpass(const int wave_s, const float* __restrict__ xin, u16* __restrict__ X, const u16* __restrict__ Y, const float* __restrict__ gpost,
;                 const float* __restrict__ gpre, u16* __restrict__ HN, float* __restrict__ outf) {
;     ...
;     if (HN) {
;       ss2 = wsum(ss2);
;       const float rs2 = rsqrtf(ss2 * (1.f / 1024.f) + 1e-6f);
; #pragma unroll
;       for (int j = 0; j < 4; ++j) {
;         const float4 g = *(const float4*)(gpre + j * 256 + lane * 4);
;         uint2 pk;
;         pk.x = pack2(x[j].x * rs2 * g.x, x[j].y * rs2 * g.y);
;         pk.y = pack2(x[j].z * rs2 * g.z, x[j].w * rs2 * g.w);
;         *(uint2*)(HN + (size_t)row * 1024 + j * 256 + lane * 4) = pk;
;       }
	v_mov_b32_e32 v44, v43
	v_mov_b32_e32 v45, v39
	v_mov_b32_e32 v26, v42
	v_mov_b32_e32 v27, v38
	v_pk_mul_f32 v[44:45], v[44:45], v[44:45]
	v_mov_b32_e32 v46, v35
	v_pk_fma_f32 v[26:27], v[26:27], v[26:27], v[44:45]
	v_mov_b32_e32 v44, v40
	v_mov_b32_e32 v45, v36
	v_pk_fma_f32 v[26:27], v[44:45], v[44:45], v[26:27]
	v_mov_b32_e32 v44, v41
	v_mov_b32_e32 v45, v37
	v_mov_b32_e32 v47, v31
	v_pk_fma_f32 v[26:27], v[44:45], v[44:45], v[26:27]
	v_mov_b32_e32 v44, v34
	v_mov_b32_e32 v45, v30
	v_pk_mul_f32 v[46:47], v[46:47], v[46:47]
	v_add_f32_e32 v0, v26, v27
	v_pk_fma_f32 v[44:45], v[44:45], v[44:45], v[46:47]
	v_mov_b32_e32 v46, v32
	v_mov_b32_e32 v47, v28
	v_pk_fma_f32 v[44:45], v[46:47], v[46:47], v[44:45]
	v_mov_b32_e32 v46, v33
	v_mov_b32_e32 v47, v29
	v_pk_fma_f32 v[44:45], v[46:47], v[46:47], v[44:45]
	s_nop 0
	v_add_f32_e32 v0, v0, v44
	v_add_f32_e32 v0, v0, v45
	v_mov_b32_e32 v26, v0
	s_nop 1
	v_permlane32_swap_b32_e32 v0, v26
	s_waitcnt lgkmcnt(0)
	v_add_f32_e32 v0, v0, v26
	v_mov_b32_e32 v26, v0
	s_nop 1
	v_permlane16_swap_b32_e32 v0, v26
	s_waitcnt lgkmcnt(0)
	v_add_f32_e32 v0, v0, v26
	s_nop 1
	v_mov_b32_dpp v26, v0 row_ror:8 row_mask:0xf bank_mask:0xf
	s_waitcnt lgkmcnt(0)
	v_add_f32_e32 v0, v0, v26
	s_nop 1
	v_mov_b32_dpp v26, v0 row_ror:4 row_mask:0xf bank_mask:0xf
	s_waitcnt lgkmcnt(0)
	v_add_f32_e32 v0, v0, v26
	s_nop 1
	v_mov_b32_dpp v26, v0 row_ror:2 row_mask:0xf bank_mask:0xf
	s_waitcnt lgkmcnt(0)
	v_add_f32_e32 v0, v0, v26
	s_nop 1
	v_mov_b32_dpp v26, v0 row_ror:1 row_mask:0xf bank_mask:0xf
	s_waitcnt lgkmcnt(0)
	v_add_f32_e32 v0, v0, v26
	v_fmamk_f32 v0, v0, 0x3a800000, v170
	v_cmp_gt_f32_e32 vcc, s16, v0
	v_mul_f32_e32 v26, 0x4b800000, v0
	s_nop 0
	v_cndmask_b32_e32 v0, v0, v26, vcc
	v_rsq_f32_e32 v0, v0
	s_nop 0
	v_mul_f32_e32 v26, 0x45800000, v0
	v_cndmask_b32_e32 v0, v0, v26, vcc
	v_pk_mul_f32 v[42:43], v[42:43], v[0:1] op_sel_hi:[1,0]
	v_pk_mul_f32 v[40:41], v[40:41], v[0:1] op_sel_hi:[1,0]
	v_lshl_add_u64 v[26:27], v[24:25], 0, s[14:15]
	v_pk_mul_f32 v[38:39], v[38:39], v[0:1] op_sel_hi:[1,0]
	v_pk_mul_f32 v[36:37], v[36:37], v[0:1] op_sel_hi:[1,0]
	v_pk_mul_f32 v[34:35], v[34:35], v[0:1] op_sel_hi:[1,0]
	v_pk_mul_f32 v[32:33], v[32:33], v[0:1] op_sel_hi:[1,0]
	v_pk_mul_f32 v[30:31], v[30:31], v[0:1] op_sel_hi:[1,0]
	v_pk_mul_f32 v[28:29], v[28:29], v[0:1] op_sel_hi:[1,0]
	s_waitcnt vmcnt(0)
	v_pk_mul_f32 v[42:43], v[100:101], v[42:43]
	v_pk_mul_f32 v[40:41], v[102:103], v[40:41]
	v_cvt_pk_bf16_f32 v42, v42, v43
	v_cvt_pk_bf16_f32 v43, v40, v41
	flat_store_dwordx2 v[26:27], v[42:43]
	v_pk_mul_f32 v[38:39], v[104:105], v[38:39]
	v_pk_mul_f32 v[36:37], v[106:107], v[36:37]
	v_cvt_pk_bf16_f32 v38, v38, v39
	v_cvt_pk_bf16_f32 v39, v36, v37
	flat_store_dwordx2 v[26:27], v[38:39] offset:512
	v_pk_mul_f32 v[34:35], v[34:35], v[108:109]
	v_pk_mul_f32 v[32:33], v[32:33], v[110:111]
	v_cvt_pk_bf16_f32 v34, v34, v35
	v_cvt_pk_bf16_f32 v35, v32, v33
	flat_store_dwordx2 v[26:27], v[34:35] offset:1024
	v_pk_mul_f32 v[30:31], v[30:31], v[112:113]
	v_pk_mul_f32 v[28:29], v[28:29], v[114:115]
	v_cvt_pk_bf16_f32 v30, v30, v31
	v_cvt_pk_bf16_f32 v31, v28, v29
	flat_store_dwordx2 v[26:27], v[30:31] offset:1536
	s_branch .LBB0_3260

; DI float bflo(unsigned u) { return __uint_as_float(u << 16); }
; DI float bfhi(unsigned u) { return __uint_as_float(u & 0xffff0000u); }
; DI void rowpass(const int wave_s, const float* __restrict__ xin, u16* __restrict__ X, const u16* __restrict__ Y, const float* __restrict__ gpost,
;                 const float* __restrict__ gpre, u16* __restrict__ HN, float* __restrict__ outf) {
;     ...
;   for (int row = blockIdx.x * 8 + wv; row < TOK; row += gridDim.x * 8) {
;     float4 x[4];
;     if (Y) {
;       float4 y[4];
;       float ss = 0.f;
; #pragma unroll
;       for (int j = 0; j < 4; ++j) {
;         const uint2 yu = *(const uint2*)(Y + (size_t)row * 1024 + j * 256 + lane * 4);
;         y[j] = make_float4(bflo(yu.x), bfhi(yu.x), bflo(yu.y), bfhi(yu.y));
;         ss += y[j].x * y[j].x + y[j].y * y[j].y + y[j].z * y[j].z + y[j].w * y[j].w;
;       }
;       ss = wsum(ss);
;       const float rs = rsqrtf(ss * (1.f / 1024.f) + 1e-6f);
; #pragma unroll
;       for (int j = 0; j < 4; ++j) {
;         const float4 g = *(const float4*)(gpost + j * 256 + lane * 4);
;         const uint2 xu = *(const uint2*)(X + (size_t)row * 1024 + j * 256 + lane * 4);
;     ...
;       for (int j = 0; j < 4; ++j) {
;         const float4 g = *(const float4*)(gpre + j * 256 + lane * 4);
.LBB0_3525:
	v_readlane_b32 s4, v254, 10
	v_readlane_b32 s5, v254, 11
	s_waitcnt lgkmcnt(0)
	s_barrier
	v_mov_b32_e32 v0, v171
	s_nop 1
	global_load_dwordx2 v[2:3], v1, s[4:5] offset:24
	s_mov_b32 s4, s6
	v_readlane_b32 s5, v254, 26
	s_add_i32 s6, s4, s5
	s_cmpk_gt_i32 s6, 0x7fff
	s_waitcnt vmcnt(0)
	v_readfirstlane_b32 s4, v3
	v_readfirstlane_b32 s5, v2
	s_cbranch_scc1 .LBB0_3530
	s_lshl_b64 s[8:9], s[12:13], 2
	s_add_u32 s8, s5, s8
	v_lshlrev_b32_e32 v18, 2, v0
	s_addc_u32 s9, s4, s9
	v_ashrrev_i32_e32 v19, 31, v18
	v_lshl_add_u64 v[22:23], v[18:19], 2, s[8:9]
	s_mov_b64 s[4:5], 0x3000
	v_lshl_add_u64 v[14:15], v[22:23], 0, s[4:5]
	s_movk_i32 s4, 0x3000
	v_add_co_u32_e32 v10, vcc, s4, v22
	v_lshlrev_b64 v[24:25], 1, v[18:19]
	s_nop 0
	v_addc_co_u32_e32 v11, vcc, 0, v23, vcc
	flat_load_dwordx4 v[2:5], v[14:15] offset:1024
	flat_load_dwordx4 v[6:9], v[14:15] offset:2048
	s_nop 0
	flat_load_dwordx4 v[10:13], v[10:11]
	s_nop 0
	flat_load_dwordx4 v[14:17], v[14:15] offset:3072
	s_cmp_lg_u64 s[0:1], 0
	s_mov_b64 s[4:5], 0x4000
	v_lshl_add_u64 v[18:19], s[14:15], 0, v[24:25]
	v_lshl_add_u64 v[20:21], s[10:11], 0, v[24:25]
	s_cselect_b64 s[8:9], -1, 0
	v_lshl_add_u64 v[22:23], v[22:23], 0, s[4:5]
	v_lshl_add_u64 v[24:25], s[0:1], 0, v[24:25]
	flat_load_dwordx4 v[100:103], v[22:23]
	flat_load_dwordx4 v[104:107], v[22:23] offset:1024
	flat_load_dwordx4 v[108:111], v[22:23] offset:2048
	flat_load_dwordx4 v[112:115], v[22:23] offset:3072
	s_branch .LBB0_3528

; DI float bflo(unsigned u) { return __uint_as_float(u << 16); }
; DI float bfhi(unsigned u) { return __uint_as_float(u & 0xffff0000u); }
; DI void rowpass(const int wave_s, const float* __restrict__ xin, u16* __restrict__ X, const u16* __restrict__ Y, const float* __restrict__ gpost,
;                 const float* __restrict__ gpre, u16* __restrict__ HN, float* __restrict__ outf) {
;     ...
;     if (Y) {
;       float4 y[4];
;       float ss = 0.f;
; #pragma unroll
;       for (int j = 0; j < 4; ++j) {
;         const uint2 yu = *(const uint2*)(Y + (size_t)row * 1024 + j * 256 + lane * 4);
;         y[j] = make_float4(bflo(yu.x), bfhi(yu.x), bflo(yu.y), bfhi(yu.y));
;         ss += y[j].x * y[j].x + y[j].y * y[j].y + y[j].z * y[j].z + y[j].w * y[j].w;
;       }
;       ss = wsum(ss);
;       const float rs = rsqrtf(ss * (1.f / 1024.f) + 1e-6f);
; #pragma unroll
;       for (int j = 0; j < 4; ++j) {
;         const float4 g = *(const float4*)(gpost + j * 256 + lane * 4);
;         const uint2 xu = *(const uint2*)(X + (size_t)row * 1024 + j * 256 + lane * 4);
;         x[j] = make_float4(bflo(xu.x), bfhi(xu.x), bflo(xu.y), bfhi(xu.y));
;         x[j].x += y[j].x * rs * g.x; x[j].y += y[j].y * rs * g.y; x[j].z += y[j].z * rs * g.z; x[j].w += y[j].w * rs * g.w;
;       }
;     } else {
; #pragma unroll
;       for (int j = 0; j < 4; ++j) x[j] = *(const float4*)(xin + (size_t)row * 1024 + j * 256 + lane * 4);
;     }
;     float ss2 = 0.f;
; #pragma unroll
;     for (int j = 0; j < 4; ++j) {
;       if (outf) *(float4*)(outf + (size_t)row * 1024 + j * 256 + lane * 4) = x[j];
;       else { uint2 xp; xp.x = pack2(x[j].x, x[j].y); xp.y = pack2(x[j].z, x[j].w); *(uint2*)(X + (size_t)row * 1024 + j * 256 + lane * 4) = xp; }
;       ss2 += x[j].x * x[j].x + x[j].y * x[j].y + x[j].z * x[j].z + x[j].w * x[j].w;
;     }
.LBB0_3528:
	s_ashr_i32 s7, s6, 31
	s_lshl_b64 s[14:15], s[6:7], 11
	v_lshl_add_u64 v[26:27], v[18:19], 0, s[14:15]
	flat_load_dwordx2 v[28:29], v[26:27]
	flat_load_dwordx2 v[30:31], v[26:27] offset:512
	flat_load_dwordx2 v[32:33], v[26:27] offset:1024
	s_nop 0
	flat_load_dwordx2 v[26:27], v[26:27] offset:1536
	v_lshl_add_u64 v[44:45], v[20:21], 0, s[14:15]
	flat_load_dwordx2 v[34:35], v[44:45]
	flat_load_dwordx2 v[36:37], v[44:45] offset:512
	flat_load_dwordx2 v[38:39], v[44:45] offset:1024
	flat_load_dwordx2 v[40:41], v[44:45] offset:1536
	s_mov_b32 s7, 0x800000
	s_andn2_b64 vcc, exec, s[8:9]
	s_waitcnt vmcnt(0) lgkmcnt(0)
	v_and_b32_e32 v43, 0xffff0000, v28
	v_and_b32_e32 v47, 0xffff0000, v30
	v_lshlrev_b32_e32 v42, 16, v28
	v_lshlrev_b32_e32 v46, 16, v30
	v_and_b32_e32 v49, 0xffff0000, v32
	v_and_b32_e32 v51, 0xffff0000, v26
	v_mov_b32_e32 v58, v43
	v_mov_b32_e32 v59, v47
	v_lshlrev_b32_e32 v28, 16, v29
	v_lshlrev_b32_e32 v30, 16, v31
	v_lshlrev_b32_e32 v48, 16, v32
	v_lshlrev_b32_e32 v50, 16, v26
	v_mov_b32_e32 v56, v42
	v_mov_b32_e32 v57, v46
	v_mov_b32_e32 v66, v49
	v_mov_b32_e32 v67, v51
	v_pk_mul_f32 v[58:59], v[58:59], v[58:59]
	v_and_b32_e32 v29, 0xffff0000, v29
	v_and_b32_e32 v31, 0xffff0000, v31
	v_lshlrev_b32_e32 v32, 16, v33
	v_lshlrev_b32_e32 v26, 16, v27
	v_mov_b32_e32 v52, v28
	v_mov_b32_e32 v53, v30
	v_mov_b32_e32 v64, v48
	v_mov_b32_e32 v65, v50
	v_pk_mul_f32 v[66:67], v[66:67], v[66:67]
	v_pk_fma_f32 v[56:57], v[56:57], v[56:57], v[58:59]
	v_and_b32_e32 v33, 0xffff0000, v33
	v_and_b32_e32 v27, 0xffff0000, v27
	v_mov_b32_e32 v54, v29
	v_mov_b32_e32 v55, v31
	v_mov_b32_e32 v60, v32
	v_mov_b32_e32 v61, v26
	v_pk_fma_f32 v[58:59], v[64:65], v[64:65], v[66:67]
	v_pk_fma_f32 v[52:53], v[52:53], v[52:53], v[56:57]
	v_mov_b32_e32 v62, v33
	v_mov_b32_e32 v63, v27
	v_pk_fma_f32 v[56:57], v[60:61], v[60:61], v[58:59]
	v_pk_fma_f32 v[52:53], v[54:55], v[54:55], v[52:53]
	v_pk_fma_f32 v[54:55], v[62:63], v[62:63], v[56:57]
	v_add_f32_e32 v0, v52, v53
	v_add_f32_e32 v0, v0, v54
	v_add_f32_e32 v0, v0, v55
	v_mov_b32_e32 v52, v0
	s_nop 1
	v_permlane32_swap_b32_e32 v0, v52
	v_lshlrev_b32_e32 v56, 16, v38
	v_lshlrev_b32_e32 v58, 16, v39
	v_and_b32_e32 v59, 0xffff0000, v39
	v_lshlrev_b32_e32 v54, 16, v36
	s_waitcnt lgkmcnt(0)
	v_add_f32_e32 v0, v0, v52
	v_mov_b32_e32 v52, v0
	s_nop 1
	v_permlane16_swap_b32_e32 v0, v52
	v_lshlrev_b32_e32 v60, 16, v40
	v_lshlrev_b32_e32 v62, 16, v41
	v_and_b32_e32 v63, 0xffff0000, v41
	s_waitcnt lgkmcnt(0)
	v_add_f32_e32 v0, v0, v52
	s_nop 1
	v_mov_b32_dpp v53, v0 row_ror:8 row_mask:0xf bank_mask:0xf
	v_lshlrev_b32_e32 v52, 16, v34
	s_waitcnt lgkmcnt(0)
	v_add_f32_e32 v0, v0, v53
	s_nop 1
	v_mov_b32_dpp v55, v0 row_ror:4 row_mask:0xf bank_mask:0xf
	v_and_b32_e32 v53, 0xffff0000, v34
	v_lshlrev_b32_e32 v34, 16, v35
	v_and_b32_e32 v35, 0xffff0000, v35
	s_waitcnt lgkmcnt(0)
	v_add_f32_e32 v0, v0, v55
	s_nop 1
	v_mov_b32_dpp v57, v0 row_ror:2 row_mask:0xf bank_mask:0xf
	v_and_b32_e32 v55, 0xffff0000, v36
	v_lshlrev_b32_e32 v36, 16, v37
	v_and_b32_e32 v37, 0xffff0000, v37
	s_waitcnt lgkmcnt(0)
	v_add_f32_e32 v0, v0, v57
	s_nop 1
	v_mov_b32_dpp v61, v0 row_ror:1 row_mask:0xf bank_mask:0xf
	v_and_b32_e32 v57, 0xffff0000, v38
	s_waitcnt lgkmcnt(0)
	v_add_f32_e32 v0, v0, v61
	v_fmamk_f32 v0, v0, 0x3a800000, v170
	v_mul_f32_e32 v38, 0x4b800000, v0
	v_cmp_gt_f32_e64 s[4:5], s7, v0
	v_and_b32_e32 v61, 0xffff0000, v40
	s_nop 0
	v_cndmask_b32_e64 v0, v0, v38, s[4:5]
	v_rsq_f32_e32 v0, v0
	s_nop 0
	v_mul_f32_e32 v38, 0x45800000, v0
	v_cndmask_b32_e64 v0, v0, v38, s[4:5]
	v_pk_mul_f32 v[38:39], v[0:1], v[42:43] op_sel_hi:[0,1]
	v_pk_mul_f32 v[28:29], v[0:1], v[28:29] op_sel_hi:[0,1]
	v_pk_mul_f32 v[46:47], v[0:1], v[46:47] op_sel_hi:[0,1]
	v_pk_mul_f32 v[30:31], v[0:1], v[30:31] op_sel_hi:[0,1]
	v_pk_mul_f32 v[48:49], v[0:1], v[48:49] op_sel_hi:[0,1]
	v_pk_mul_f32 v[32:33], v[0:1], v[32:33] op_sel_hi:[0,1]
	v_pk_mul_f32 v[50:51], v[0:1], v[50:51] op_sel_hi:[0,1]
	v_pk_mul_f32 v[26:27], v[0:1], v[26:27] op_sel_hi:[0,1]
	v_pk_fma_f32 v[42:43], v[10:11], v[38:39], v[52:53]
	v_pk_fma_f32 v[40:41], v[12:13], v[28:29], v[34:35]
	v_pk_fma_f32 v[38:39], v[2:3], v[46:47], v[54:55]
	v_pk_fma_f32 v[36:37], v[4:5], v[30:31], v[36:37]
	v_pk_fma_f32 v[34:35], v[6:7], v[48:49], v[56:57]
	v_pk_fma_f32 v[32:33], v[32:33], v[8:9], v[58:59]
	v_pk_fma_f32 v[30:31], v[50:51], v[14:15], v[60:61]
	v_pk_fma_f32 v[28:29], v[26:27], v[16:17], v[62:63]
	v_cvt_pk_bf16_f32 v26, v42, v43
	v_cvt_pk_bf16_f32 v27, v40, v41
	v_cvt_pk_bf16_f32 v46, v38, v39
	v_cvt_pk_bf16_f32 v47, v36, v37
	v_cvt_pk_bf16_f32 v48, v34, v35
	v_cvt_pk_bf16_f32 v49, v32, v33
	v_cvt_pk_bf16_f32 v50, v30, v31
	v_cvt_pk_bf16_f32 v51, v28, v29
	flat_store_dwordx2 v[44:45], v[26:27]
	flat_store_dwordx2 v[44:45], v[46:47] offset:512
	flat_store_dwordx2 v[44:45], v[48:49] offset:1024
	flat_store_dwordx2 v[44:45], v[50:51] offset:1536
	s_cbranch_vccnz .LBB0_3527
; DI void rowpass(const int wave_s, const float* __restrict__ xin, u16* __restrict__ X, const u16* __restrict__ Y, const float* __restrict__ gpost,
;                 const float* __restrict__ gpre, u16* __restrict__ HN, float* __restrict__ outf) {
;     ...
;     if (HN) {
;       ss2 = wsum(ss2);
;       const float rs2 = rsqrtf(ss2 * (1.f / 1024.f) + 1e-6f);
; #pragma unroll
;       for (int j = 0; j < 4; ++j) {
;         const float4 g = *(const float4*)(gpre + j * 256 + lane * 4);
;         uint2 pk;
;         pk.x = pack2(x[j].x * rs2 * g.x, x[j].y * rs2 * g.y);
;         pk.y = pack2(x[j].z * rs2 * g.z, x[j].w * rs2 * g.w);
;         *(uint2*)(HN + (size_t)row * 1024 + j * 256 + lane * 4) = pk;
;       }
	v_mov_b32_e32 v44, v43
	v_mov_b32_e32 v45, v39
	v_mov_b32_e32 v26, v42
	v_mov_b32_e32 v27, v38
	v_pk_mul_f32 v[44:45], v[44:45], v[44:45]
	v_mov_b32_e32 v46, v35
	v_pk_fma_f32 v[26:27], v[26:27], v[26:27], v[44:45]
	v_mov_b32_e32 v44, v40
	v_mov_b32_e32 v45, v36
	v_pk_fma_f32 v[26:27], v[44:45], v[44:45], v[26:27]
	v_mov_b32_e32 v44, v41
	v_mov_b32_e32 v45, v37
	v_mov_b32_e32 v47, v31
	v_pk_fma_f32 v[26:27], v[44:45], v[44:45], v[26:27]
	v_mov_b32_e32 v44, v34
	v_mov_b32_e32 v45, v30
	v_pk_mul_f32 v[46:47], v[46:47], v[46:47]
	v_add_f32_e32 v0, v26, v27
	v_pk_fma_f32 v[44:45], v[44:45], v[44:45], v[46:47]
	v_mov_b32_e32 v46, v32
	v_mov_b32_e32 v47, v28
	v_pk_fma_f32 v[44:45], v[46:47], v[46:47], v[44:45]
	v_mov_b32_e32 v46, v33
	v_mov_b32_e32 v47, v29
	v_pk_fma_f32 v[44:45], v[46:47], v[46:47], v[44:45]
	s_nop 0
	v_add_f32_e32 v0, v0, v44
	v_add_f32_e32 v0, v0, v45
	v_mov_b32_e32 v26, v0
	s_nop 1
	v_permlane32_swap_b32_e32 v0, v26
	s_waitcnt lgkmcnt(0)
	v_add_f32_e32 v0, v0, v26
	v_mov_b32_e32 v26, v0
	s_nop 1
	v_permlane16_swap_b32_e32 v0, v26
	s_waitcnt lgkmcnt(0)
	v_add_f32_e32 v0, v0, v26
	s_nop 1
	v_mov_b32_dpp v26, v0 row_ror:8 row_mask:0xf bank_mask:0xf
	s_waitcnt lgkmcnt(0)
	v_add_f32_e32 v0, v0, v26
	s_nop 1
	v_mov_b32_dpp v26, v0 row_ror:4 row_mask:0xf bank_mask:0xf
	s_waitcnt lgkmcnt(0)
	v_add_f32_e32 v0, v0, v26
	s_nop 1
	v_mov_b32_dpp v26, v0 row_ror:2 row_mask:0xf bank_mask:0xf
	s_waitcnt lgkmcnt(0)
	v_add_f32_e32 v0, v0, v26
	s_nop 1
	v_mov_b32_dpp v26, v0 row_ror:1 row_mask:0xf bank_mask:0xf
	s_waitcnt lgkmcnt(0)
	v_add_f32_e32 v0, v0, v26
	v_fmamk_f32 v0, v0, 0x3a800000, v170
	v_cmp_gt_f32_e32 vcc, s7, v0
	v_mul_f32_e32 v26, 0x4b800000, v0
	s_nop 0
	v_cndmask_b32_e32 v0, v0, v26, vcc
	v_rsq_f32_e32 v0, v0
	s_nop 0
	v_mul_f32_e32 v26, 0x45800000, v0
	v_cndmask_b32_e32 v0, v0, v26, vcc
	v_pk_mul_f32 v[42:43], v[42:43], v[0:1] op_sel_hi:[1,0]
	v_pk_mul_f32 v[40:41], v[40:41], v[0:1] op_sel_hi:[1,0]
	v_lshl_add_u64 v[26:27], v[24:25], 0, s[14:15]
	v_pk_mul_f32 v[38:39], v[38:39], v[0:1] op_sel_hi:[1,0]
	v_pk_mul_f32 v[36:37], v[36:37], v[0:1] op_sel_hi:[1,0]
	v_pk_mul_f32 v[34:35], v[34:35], v[0:1] op_sel_hi:[1,0]
	v_pk_mul_f32 v[32:33], v[32:33], v[0:1] op_sel_hi:[1,0]
	v_pk_mul_f32 v[30:31], v[30:31], v[0:1] op_sel_hi:[1,0]
	v_pk_mul_f32 v[28:29], v[28:29], v[0:1] op_sel_hi:[1,0]
	s_waitcnt vmcnt(0)
	v_pk_mul_f32 v[42:43], v[100:101], v[42:43]
	v_pk_mul_f32 v[40:41], v[102:103], v[40:41]
	v_cvt_pk_bf16_f32 v42, v42, v43
	v_cvt_pk_bf16_f32 v43, v40, v41
	flat_store_dwordx2 v[26:27], v[42:43]
	v_pk_mul_f32 v[38:39], v[104:105], v[38:39]
	v_pk_mul_f32 v[36:37], v[106:107], v[36:37]
	v_cvt_pk_bf16_f32 v38, v38, v39
	v_cvt_pk_bf16_f32 v39, v36, v37
	flat_store_dwordx2 v[26:27], v[38:39] offset:512
	v_pk_mul_f32 v[34:35], v[34:35], v[108:109]
	v_pk_mul_f32 v[32:33], v[32:33], v[110:111]
	v_cvt_pk_bf16_f32 v34, v34, v35
	v_cvt_pk_bf16_f32 v35, v32, v33
	flat_store_dwordx2 v[26:27], v[34:35] offset:1024
	v_pk_mul_f32 v[30:31], v[30:31], v[112:113]
	v_pk_mul_f32 v[28:29], v[28:29], v[114:115]
	v_cvt_pk_bf16_f32 v30, v30, v31
	v_cvt_pk_bf16_f32 v31, v28, v29
	flat_store_dwordx2 v[26:27], v[30:31] offset:1536
	s_branch .LBB0_3527
